# v54 + per-token rstd table moved from LDS 0x20000 to 0x20400 (clear of UP epilogue staging) and UP epilogue quarter-0 leading barrier removed
# baseline (speedup 1.0000x reference)
; template <int MODE>
; DI void phase_gemm(const Params& p, int l, char* smem) {
;     ...
;   const int G = gridDim.x;
;   const bool xmap = (G & 7) == 0;
;   const int xcd = blockIdx.x & 7, nb = xmap ? (G >> 3) : G, tot = xmap ? 32 * NT : 256 * NT;
;   for (int L = xmap ? (int)(blockIdx.x >> 3) : (int)blockIdx.x; L < tot; L += nb) {
;     int mp = (xmap ? xcd * 32 : 0) + L / NT, nt = L % NT;
; __global__ void __launch_bounds__(512, 2) mega(Params p) {
;   __shared__ __attribute__((aligned(16))) char smem[163328];
;   cg::grid_group grid = cg::this_grid();
;   for (int ph = p.ph_lo; ph < p.ph_hi; ++ph) {
;     if (ph == 0) phase_prep(p, smem);
;     else if (ph == 25) phase_final(p);
;     else {
;       const int l = (ph - 1) / 6, k = (ph - 1) % 6;
;       if (k == 0) phase_gemm<MODE_PROJ>(p, l, smem);
;       else if (k == 1) phase_cmp(p, l, smem);
;       else if (k == 2) phase_attn(p, l, smem);
;       else if (k == 3) phase_gemm<MODE_OUT>(p, l, smem);
;       else if (k == 4) phase_gemm<MODE_UP>(p, l, smem);
;       else phase_gemm<MODE_DOWN>(p, l, smem);
;     }
;     if (ph + 1 < p.ph_hi) {
;       if (ph == p.ph_lo || (gridDim.x & 7u) != 0u) grid.sync();
;       else grid_bar2((unsigned*)(p.ws + OFF_CTR + 1024), (unsigned)(ph - p.ph_lo), gridDim.x >> 3);
;     }
;   }
; }
_Z4mega6Params:
	s_load_dwordx2 s[70:71], s[0:1], 0xb0
	s_waitcnt lgkmcnt(0)
	s_cmp_ge_i32 s70, s71
	s_cbranch_scc1 .LBB0_959
	s_mov_b32 s68, s2
	s_load_dword s69, s[0:1], 0xb8
	s_load_dwordx2 s[2:3], s[0:1], 0xc4
	s_lshl_b32 s7, s68, 5
	s_movk_i32 s72, 0x80
	s_load_dwordx4 s[16:19], s[0:1], 0x0
	s_load_dwordx8 s[20:27], s[0:1], 0x10
	s_load_dwordx16 s[44:59], s[0:1], 0x38
	s_load_dwordx2 s[78:79], s[0:1], 0xa8
	s_load_dwordx4 s[28:31], s[0:1], 0x98
	s_waitcnt lgkmcnt(0)
	s_and_b32 s6, s69, 7
	s_cmp_eq_u32 s6, 0
	s_cselect_b64 s[4:5], -1, 0
	s_and_b64 s[4:5], s[4:5], exec
	s_movk_i32 s4, 0x160
	s_cselect_b32 s73, s72, 0x400
	s_cselect_b32 s74, s4, 0xb00
	s_and_b32 s75, s7, 0xe0
	s_cmp_eq_u32 s6, 0
	s_cselect_b64 s[4:5], -1, 0
	s_and_b64 s[4:5], s[4:5], exec
	s_cselect_b32 s76, s75, 0
	s_lshr_b32 s7, s68, 3
	s_cmp_eq_u32 s6, 0
	s_cselect_b64 s[4:5], -1, 0
	s_movk_i32 s77, 0x200
	s_and_b64 s[4:5], s[4:5], exec
	s_cselect_b32 s11, s77, 0x1000
	s_cselect_b32 s12, s7, s68
	s_ashr_i32 s7, s69, 3
	s_cmp_eq_u32 s6, 0
	s_cselect_b64 s[14:15], -1, 0
	v_writelane_b32 v247, s28, 0
	s_and_b64 s[4:5], s[14:15], exec
	s_cselect_b32 s60, s7, s69
	v_writelane_b32 v247, s29, 1
	v_writelane_b32 v247, s30, 2
	s_add_u32 s4, s0, 0xb8
	v_writelane_b32 v247, s31, 3
	s_addc_u32 s5, s1, 0
	v_writelane_b32 v247, s4, 4
	s_and_b32 s3, s3, 0xffff
	s_lshr_b32 s6, s2, 16
	v_writelane_b32 v247, s5, 5
	s_add_u32 s66, s78, 0x6240000
	v_writelane_b32 v247, s3, 6
	s_addc_u32 s67, s79, 0
	s_lshl_b32 s13, s68, 3
	s_lshl_b32 s3, s69, 3
	s_lshl_b32 s28, s69, 5
	s_load_dwordx8 s[36:43], s[0:1], 0x78
	s_load_dwordx2 s[4:5], s[0:1], 0x30
	s_add_u32 s0, s78, 0x6641000
	s_addc_u32 s1, s79, 0
	v_writelane_b32 v247, s0, 7
	s_cmpk_lt_i32 s68, 0x3110
	s_mov_b32 s97, 0
	v_writelane_b32 v247, s1, 8
	s_cselect_b64 s[0:1], -1, 0
	v_writelane_b32 v247, s0, 9
	v_and_b32_e32 v152, 0x3ff, v0
	v_bfe_u32 v1, v0, 10, 10
	v_writelane_b32 v247, s1, 10
	s_add_u32 s0, s78, 0x6200000
	s_addc_u32 s1, s79, 0
	v_writelane_b32 v247, s0, 11
	v_bfe_u32 v0, v0, 20, 10
	v_mad_u32_u24 v153, v0, s6, v1
	v_writelane_b32 v247, s1, 12
	s_add_u32 s0, s78, 0x5e00000
	v_writelane_b32 v247, s0, 13
	s_addc_u32 s0, s79, 0
	v_writelane_b32 v247, s0, 14
	s_add_u32 s0, s78, 0x3e00000
	v_writelane_b32 v247, s0, 15
	s_addc_u32 s0, s79, 0
	v_writelane_b32 v247, s0, 16
	s_add_u32 s0, s78, 0x1e00000
	v_writelane_b32 v247, s0, 17
	s_addc_u32 s0, s79, 0
	v_writelane_b32 v247, s0, 18
	s_waitcnt lgkmcnt(0)
	v_writelane_b32 v247, s36, 19
	s_cmp_lg_u64 s[38:39], 0
	s_cselect_b64 s[0:1], -1, 0
	v_writelane_b32 v247, s37, 20
	v_writelane_b32 v247, s38, 21
	v_writelane_b32 v247, s39, 22
	v_writelane_b32 v247, s40, 23
	v_writelane_b32 v247, s41, 24
	v_writelane_b32 v247, s42, 25
	v_writelane_b32 v247, s43, 26
	v_writelane_b32 v247, s0, 27
	s_mov_b64 s[42:43], s[26:27]
	s_mov_b64 s[40:41], s[24:25]
	v_writelane_b32 v247, s1, 28
	s_add_u32 s0, s78, 0x1600000
	v_writelane_b32 v247, s0, 29
	s_addc_u32 s0, s79, 0
	s_cmp_lg_u64 s[58:59], 0
	v_writelane_b32 v247, s0, 30
	s_cselect_b64 s[0:1], -1, 0
	v_writelane_b32 v247, s0, 31
	s_cmp_lg_u64 s[18:19], 0
	s_mov_b64 s[36:37], s[20:21]
	v_writelane_b32 v247, s1, 32
	s_cselect_b64 s[0:1], -1, 0
	v_writelane_b32 v247, s0, 33
	s_cmp_lt_u32 s68, 64
	v_or3_b32 v0, v152, v1, v0
	v_writelane_b32 v247, s1, 34
	s_cselect_b64 s[0:1], -1, 0
	v_writelane_b32 v247, s0, 35
	s_lshr_b32 s96, s68, 4
	s_and_b32 s2, s68, 8
	v_writelane_b32 v247, s1, 36
	v_writelane_b32 v247, s36, 37
	s_lshl_b64 s[0:1], s[96:97], 13
	s_cmp_eq_u32 s2, 0
	v_writelane_b32 v247, s37, 38
	v_writelane_b32 v247, s38, 39
	v_writelane_b32 v247, s39, 40
	v_writelane_b32 v247, s40, 41
	v_writelane_b32 v247, s41, 42
	v_writelane_b32 v247, s42, 43
	v_writelane_b32 v247, s43, 44
	s_cselect_b32 s9, s25, s45
	v_writelane_b32 v247, s44, 45
	s_cselect_b32 s7, s23, s5
	s_cselect_b32 s8, s22, s4
	v_writelane_b32 v247, s45, 46
	v_writelane_b32 v247, s46, 47
	v_writelane_b32 v247, s47, 48
	v_writelane_b32 v247, s48, 49
	v_writelane_b32 v247, s49, 50
	v_writelane_b32 v247, s50, 51
	v_writelane_b32 v247, s51, 52
	v_writelane_b32 v247, s52, 53
	v_writelane_b32 v247, s53, 54
	v_writelane_b32 v247, s54, 55
	v_writelane_b32 v247, s55, 56
	v_writelane_b32 v247, s56, 57
	s_cselect_b32 s10, s24, s44
	s_lshl_b32 s4, s68, 8
	s_mov_b32 s36, s3
	v_writelane_b32 v247, s57, 58
	s_lshl_b64 s[2:3], s[96:97], 20
	s_and_b32 s20, s4, 0x700
	v_writelane_b32 v247, s58, 59
	s_add_u32 s4, s78, 0x6220000
	v_writelane_b32 v247, s59, 60
	s_addc_u32 s5, s79, 0
	v_writelane_b32 v247, s4, 61
	v_mbcnt_lo_u32_b32 v202, -1, 0
	s_mov_b32 s61, 0xffff
	v_writelane_b32 v247, s5, 62
	s_lshl_b32 s4, s68, 9
	s_cmp_eq_u32 s68, 0
	v_writelane_b32 v247, s4, 63
	s_cselect_b64 s[4:5], -1, 0
	v_writelane_b32 v246, s4, 0
	v_mov_b32_e32 v1, 0
	v_mov_b32_e32 v154, 0x358637bd
	v_writelane_b32 v246, s5, 1
	s_add_u32 s4, s78, 0x6640000
	s_addc_u32 s5, s79, 0
	v_writelane_b32 v246, s4, 2
	s_cmp_lt_i32 s12, s11
	s_movk_i32 s33, 0x210
	v_writelane_b32 v246, s5, 3
	v_writelane_b32 v246, s11, 4
	s_cselect_b64 s[4:5], -1, 0
	v_writelane_b32 v246, s4, 5
	s_cmp_eq_u32 s60, 32
	s_movk_i32 s80, 0x50
	v_writelane_b32 v246, s5, 6
	s_cselect_b64 s[4:5], -1, 0
	v_writelane_b32 v246, s14, 7
	s_and_b64 s[4:5], s[14:15], s[4:5]
	v_mov_b32_e32 v155, 0x3f4ccccd
	v_writelane_b32 v246, s15, 8
	v_writelane_b32 v246, s4, 9
	v_mov_b32_e32 v200, 1
	s_movk_i32 s91, 0xf00
	v_writelane_b32 v246, s5, 10
	s_or_b32 s4, s75, 24
	v_writelane_b32 v246, s4, 11
	s_add_u32 s4, s78, 0x6440000
	v_writelane_b32 v246, s4, 12
	s_addc_u32 s4, s79, 0
	v_writelane_b32 v246, s4, 13
	s_add_u32 s4, s78, 0xe641000
	s_addc_u32 s5, s79, 0
; template <int MODE>
; DI void gemm_tile(const Params& p, const bf16_t* __restrict__ A, const bf16_t* __restrict__ Bt, int K, int brow, int bcol, int mp, int nt, bool vt, char* smem) {
;     ...
;   float* rsl = (float*)(smem + 131072);
; __global__ void __launch_bounds__(512, 2) mega(Params p) {
;   __shared__ __attribute__((aligned(16))) char smem[163328];
;   cg::grid_group grid = cg::this_grid();
;   for (int ph = p.ph_lo; ph < p.ph_hi; ++ph) {
;     if (ph == 0) phase_prep(p, smem);
;     else if (ph == 25) phase_final(p);
;     else {
;       const int l = (ph - 1) / 6, k = (ph - 1) % 6;
;       if (k == 0) phase_gemm<MODE_PROJ>(p, l, smem);
;       else if (k == 1) phase_cmp(p, l, smem);
;       else if (k == 2) phase_attn(p, l, smem);
;       else if (k == 3) phase_gemm<MODE_OUT>(p, l, smem);
;       else if (k == 4) phase_gemm<MODE_UP>(p, l, smem);
;       else phase_gemm<MODE_DOWN>(p, l, smem);
;     }
;     if (ph + 1 < p.ph_hi) {
;       if (ph == p.ph_lo || (gridDim.x & 7u) != 0u) grid.sync();
;       else grid_bar2((unsigned*)(p.ws + OFF_CTR + 1024), (unsigned)(ph - p.ph_lo), gridDim.x >> 3);
;     }
;   }
; }
	v_writelane_b32 v246, s4, 14
	s_movk_i32 s81, 0x1200
	s_movk_i32 s86, 0x2600
	v_writelane_b32 v246, s5, 15
	s_add_u32 s4, s78, 0x23b41000
	s_addc_u32 s5, s79, 0
	v_writelane_b32 v246, s4, 16
	s_cmp_lt_i32 s12, s73
	s_mov_b32 s85, 0xff61b1e6
	v_writelane_b32 v246, s5, 17
	s_cselect_b64 s[4:5], -1, 0
	v_writelane_b32 v246, s4, 18
	s_mov_b32 s92, 0xf149f2ca
	s_mov_b32 s82, 0xefa18f08
	v_writelane_b32 v246, s5, 19
	s_add_u32 s4, s78, 0x1d641000
	s_addc_u32 s5, s79, 0
	v_writelane_b32 v246, s4, 20
	v_mov_b32_e32 v201, 0x27e00
	s_brev_b32 s83, -2
	v_writelane_b32 v246, s5, 21
	s_add_u32 s4, s78, 0x23641000
	s_addc_u32 s5, s79, 0
	v_writelane_b32 v246, s4, 22
	s_mov_b64 s[88:89], 0xa00
	s_mov_b32 s90, 0x3e8293ee
	v_writelane_b32 v246, s5, 23
	s_add_u32 s4, s78, 0x23a41000
	v_writelane_b32 v246, s4, 24
	s_addc_u32 s4, s79, 0
	v_writelane_b32 v246, s4, 25
	s_add_u32 s4, s78, 0x23ac1000
	s_addc_u32 s5, s79, 0
	v_writelane_b32 v246, s4, 26
	v_mbcnt_hi_u32_b32 v203, -1, v202
	v_mov_b32_e32 v204, 0x20400
	v_writelane_b32 v246, s5, 27
	s_lshl_b32 s4, s6, 8
	s_cmpk_lt_i32 s68, 0x100
	v_writelane_b32 v246, s4, 28
	s_cselect_b64 s[4:5], -1, 0
	v_writelane_b32 v246, s4, 29
	s_cmp_lt_i32 s12, s74
	v_mov_b32_e32 v205, 0x10000
	v_writelane_b32 v246, s5, 30
	v_writelane_b32 v246, s12, 31
	s_cselect_b64 s[4:5], -1, 0
	v_writelane_b32 v246, s4, 32
	v_mov_b32_e32 v206, 0x20600
	v_mov_b32_e32 v207, 3
	v_writelane_b32 v246, s5, 33
	v_cmp_eq_u32_e64 s[4:5], 0, v0
	v_mov_b32_e32 v208, 0xf149f2ca
	v_mov_b32_e32 v209, 0x4e6e6b28
	v_writelane_b32 v246, s4, 34
	v_mov_b32_e32 v210, 0xff800000
	v_mov_b32_e32 v211, 2
	v_writelane_b32 v246, s5, 35
	s_lshr_b32 s4, s69, 3
	s_lshl_b32 s5, s75, 2
	s_add_u32 s5, s78, s5
	s_addc_u32 s6, s79, 0
	s_add_u32 s14, s5, 0x6640400
	s_addc_u32 s15, s6, 0
	v_writelane_b32 v246, s14, 36
	s_add_i32 s4, s4, -1
	v_mov_b32_e32 v212, 0xf00
	v_writelane_b32 v246, s15, 37
	v_writelane_b32 v246, s4, 38
	s_add_u32 s4, s78, 0x6640800
	s_addc_u32 s5, s79, 0
	v_writelane_b32 v246, s4, 39
	s_nop 1
	v_writelane_b32 v246, s5, 40
	s_add_u32 s4, s78, 0x6640880
	s_addc_u32 s5, s79, 0
	v_writelane_b32 v246, s4, 41
	s_nop 1
	v_writelane_b32 v246, s5, 42
	s_add_u32 s4, s78, 0x6640900
	s_addc_u32 s5, s79, 0
	v_writelane_b32 v246, s4, 43
	s_nop 1
	v_writelane_b32 v246, s5, 44
	s_add_u32 s4, s78, 0x6640980
	s_addc_u32 s5, s79, 0
	v_writelane_b32 v246, s4, 45
	s_nop 1
	v_writelane_b32 v246, s5, 46
	s_add_u32 s4, s78, 0x6640a00
	s_addc_u32 s5, s79, 0
	v_writelane_b32 v246, s4, 47
	s_nop 1
	v_writelane_b32 v246, s5, 48
	s_add_u32 s4, s78, 0x6640a80
	s_addc_u32 s5, s79, 0
	v_writelane_b32 v246, s4, 49
	s_nop 1
	v_writelane_b32 v246, s5, 50
	s_add_u32 s4, s78, 0x6640b00
	s_addc_u32 s5, s79, 0
	v_writelane_b32 v246, s4, 51
	s_nop 1
	v_writelane_b32 v246, s5, 52
	s_add_u32 s4, s78, 0x6640b80
	s_addc_u32 s5, s79, 0
	v_writelane_b32 v246, s4, 53
	s_nop 1
	v_writelane_b32 v246, s5, 54
	s_add_u32 s4, s78, 0x6640c00
	s_addc_u32 s5, s79, 0
	v_writelane_b32 v246, s4, 55
	s_ashr_i32 s29, s28, 31
	s_lshl_b32 s37, s69, 4
	v_writelane_b32 v246, s5, 56
	s_lshl_b64 s[4:5], s[28:29], 12
	v_writelane_b32 v246, s4, 57
	s_nop 1
	v_writelane_b32 v246, s5, 58
	s_lshl_b64 s[4:5], s[28:29], 11
	v_writelane_b32 v246, s4, 59
	s_nop 1
	v_writelane_b32 v246, s5, 60
	s_mov_b32 s4, s28
	v_writelane_b32 v246, s4, 61
	s_nop 1
	v_writelane_b32 v246, s5, 62
	s_lshl_b64 s[4:5], s[28:29], 5
	v_writelane_b32 v246, s4, 63
	s_nop 1
	v_writelane_b32 v245, s5, 0
	s_mul_i32 s4, s69, 24
	v_writelane_b32 v245, s4, 1
	v_writelane_b32 v245, s13, 2
	s_add_i32 s4, s13, s36
	v_writelane_b32 v245, s4, 3
	s_lshl_b32 s4, s68, 6
	v_writelane_b32 v245, s4, 4
	s_lshl_b32 s4, s68, 1
	v_writelane_b32 v245, s4, 5
	s_lshl_b32 s4, s68, 2
	v_writelane_b32 v245, s4, 6
	s_add_i32 s4, s20, -16
	s_add_u32 s2, s10, s2
	s_addc_u32 s3, s9, s3
	s_add_u32 s2, s2, 0x1e00
	s_addc_u32 s3, s3, 0
	v_writelane_b32 v245, s20, 7
	s_add_u32 s0, s8, s0
	v_writelane_b32 v245, s4, 8
	s_addc_u32 s1, s7, s1
	v_writelane_b32 v245, s2, 9
	s_add_u32 s0, s0, 60
	s_addc_u32 s1, s1, 0
	v_writelane_b32 v245, s3, 10
	v_writelane_b32 v245, s0, 11
	s_mov_b32 s8, s70
	s_nop 0
	v_writelane_b32 v245, s1, 12
	s_add_u32 s0, s16, 0x800
	v_writelane_b32 v245, s16, 13
	s_addc_u32 s1, s17, 0
	s_nop 0
	v_writelane_b32 v245, s17, 14
	v_writelane_b32 v245, s18, 15
	v_writelane_b32 v245, s19, 16
	v_writelane_b32 v245, s0, 17
	s_nop 1
	v_writelane_b32 v245, s1, 18
	s_add_u32 s0, s78, 0x1e40000
	v_writelane_b32 v245, s0, 19
	s_addc_u32 s0, s79, 0
	v_writelane_b32 v245, s0, 20
	s_add_u32 s0, s78, 0x1640000
	v_writelane_b32 v245, s0, 21
	s_addc_u32 s0, s79, 0
	v_writelane_b32 v245, s0, 22
	s_add_u32 s0, s78, 0xe641200
	s_addc_u32 s1, s79, 0
	v_writelane_b32 v245, s0, 23
	s_nop 1
	v_writelane_b32 v245, s1, 24
	s_add_u32 s0, s78, 0x5e00100
	s_addc_u32 s1, s79, 0
	v_writelane_b32 v245, s0, 25
	s_bitcmp1_b32 s68, 0
	s_nop 0
	v_writelane_b32 v245, s1, 26
	s_cselect_b64 s[0:1], -1, 0
	v_writelane_b32 v245, s0, 27
	s_bitcmp1_b32 s69, 0
	s_nop 0
	v_writelane_b32 v245, s1, 28
	s_cselect_b64 s[0:1], -1, 0
	v_writelane_b32 v245, s0, 29
	s_nop 1
	v_writelane_b32 v245, s1, 30
	s_add_u32 s0, s78, 0x3f00000
	v_writelane_b32 v245, s0, 31
	s_addc_u32 s0, s79, 0
	v_writelane_b32 v245, s0, 32
	s_mov_b32 s1, 0x41880000
	v_writelane_b32 v245, s0, 33
	s_nop 1
	v_writelane_b32 v245, s1, 34
	s_mov_b32 s1, 0x41800000
	v_writelane_b32 v245, s0, 35
	s_nop 1
	v_writelane_b32 v245, s1, 36
	v_writelane_b32 v245, s60, 37
	v_writelane_b32 v245, s66, 38
	s_nop 1
	v_writelane_b32 v245, s67, 39
	v_writelane_b32 v245, s36, 40
	v_writelane_b32 v245, s37, 41
	v_writelane_b32 v245, s68, 42
	v_writelane_b32 v245, s70, 43
	s_nop 1
	v_writelane_b32 v245, s71, 44
	v_writelane_b32 v245, s69, 45
	v_writelane_b32 v245, s73, 46
	v_writelane_b32 v245, s74, 47
	v_writelane_b32 v245, s75, 48
	v_writelane_b32 v245, s76, 49
	v_writelane_b32 v245, s78, 50
	s_nop 1
	v_writelane_b32 v245, s79, 51
	s_branch .LBB0_6

; DI unsigned pk2(float a, float b) { f32x2 v = {a, b}; bf2_t r = __builtin_convertvector(v, bf2_t); return __builtin_bit_cast(unsigned, r); }
; template <int MODE>
; DI void gemm_tile(const Params& p, const bf16_t* __restrict__ A, const bf16_t* __restrict__ Bt, int K, int brow, int bcol, int mp, int nt, bool vt, char* smem) {
;     ...
;   for (int ai = 0; ai < 2; ++ai)
; #pragma unroll
;     for (int bj = 0; bj < 2; ++bj) {
; #pragma unroll
;       for (int m = 0; m < 4; ++m)
; #pragma unroll
;         for (int n = 0; n < 2; ++n) *(f32x4*)(st + (wc * 32 + n * 16 + fr) * 132 + wr * 64 + m * 16 + fq * 4) = acc[ai][bj][m][n];
;       __syncthreads();
;     ...
;         } else if (MODE == MODE_UP) {
;           const int tok = m0 + bj * 128 + y, col = n0 + ai * 128 + x4;
;           const float rs = rsl[bj * 128 + y];
;           const float a0 = fmaxf(v[0] * rs, 0.f), a1 = fmaxf(v[1] * rs, 0.f), a2 = fmaxf(v[2] * rs, 0.f), a3 = fmaxf(v[3] * rs, 0.f);
;           u32x2 o = {pk2(a0 * a0, a1 * a1), pk2(a2 * a2, a3 * a3)};
;           *(u32x2*)((bf16_t*)(p.ws + OFF_U) + (size_t)tok * DFF + col) = o;
.Lup_noearly:
	s_waitcnt lgkmcnt(0)
	s_nop 0
	v_mul_f32_e32 v98, v98, v144
	v_mul_f32_e32 v99, v99, v144
	v_mul_f32_e32 v100, v100, v144
	v_mul_f32_e32 v101, v101, v144
	v_max_f32_e32 v98, 0, v98
	v_max_f32_e32 v99, 0, v99
	v_max_f32_e32 v100, 0, v100
	v_max_f32_e32 v101, 0, v101
	v_pk_mul_f32 v[98:99], v[98:99], v[98:99]
	v_pk_mul_f32 v[100:101], v[100:101], v[100:101]
	v_cvt_pk_bf16_f32 v98, v98, v99
	v_cvt_pk_bf16_f32 v99, v100, v101
	ds_write_b64 v134, v[98:99]
	v_mul_f32_e32 v102, v102, v145
	v_mul_f32_e32 v103, v103, v145
	v_mul_f32_e32 v104, v104, v145
	v_mul_f32_e32 v105, v105, v145
	v_max_f32_e32 v102, 0, v102
	v_max_f32_e32 v103, 0, v103
	v_max_f32_e32 v104, 0, v104
	v_max_f32_e32 v105, 0, v105
	v_pk_mul_f32 v[102:103], v[102:103], v[102:103]
	v_pk_mul_f32 v[104:105], v[104:105], v[104:105]
	v_cvt_pk_bf16_f32 v102, v102, v103
	v_cvt_pk_bf16_f32 v103, v104, v105
	ds_write_b64 v134, v[102:103] offset:4224
	v_mul_f32_e32 v106, v106, v144
	v_mul_f32_e32 v107, v107, v144
	v_mul_f32_e32 v108, v108, v144
	v_mul_f32_e32 v109, v109, v144
	v_max_f32_e32 v106, 0, v106
	v_max_f32_e32 v107, 0, v107
	v_max_f32_e32 v108, 0, v108
	v_max_f32_e32 v109, 0, v109
	v_pk_mul_f32 v[106:107], v[106:107], v[106:107]
	v_pk_mul_f32 v[108:109], v[108:109], v[108:109]
	v_cvt_pk_bf16_f32 v106, v106, v107
	v_cvt_pk_bf16_f32 v107, v108, v109
	ds_write_b64 v134, v[106:107] offset:32
	v_mul_f32_e32 v110, v110, v145
	v_mul_f32_e32 v111, v111, v145
	v_mul_f32_e32 v112, v112, v145
	v_mul_f32_e32 v113, v113, v145
	v_max_f32_e32 v110, 0, v110
	v_max_f32_e32 v111, 0, v111
	v_max_f32_e32 v112, 0, v112
	v_max_f32_e32 v113, 0, v113
	v_pk_mul_f32 v[110:111], v[110:111], v[110:111]
	v_pk_mul_f32 v[112:113], v[112:113], v[112:113]
	v_cvt_pk_bf16_f32 v110, v110, v111
	v_cvt_pk_bf16_f32 v111, v112, v113
	ds_write_b64 v134, v[110:111] offset:4256
	v_mul_f32_e32 v114, v114, v144
	v_mul_f32_e32 v115, v115, v144
	v_mul_f32_e32 v116, v116, v144
	v_mul_f32_e32 v117, v117, v144
	v_max_f32_e32 v114, 0, v114
	v_max_f32_e32 v115, 0, v115
	v_max_f32_e32 v116, 0, v116
	v_max_f32_e32 v117, 0, v117
	v_pk_mul_f32 v[114:115], v[114:115], v[114:115]
	v_pk_mul_f32 v[116:117], v[116:117], v[116:117]
	v_cvt_pk_bf16_f32 v114, v114, v115
	v_cvt_pk_bf16_f32 v115, v116, v117
	ds_write_b64 v134, v[114:115] offset:64
	v_mul_f32_e32 v118, v118, v145
	v_mul_f32_e32 v119, v119, v145
	v_mul_f32_e32 v120, v120, v145
	v_mul_f32_e32 v121, v121, v145
	v_max_f32_e32 v118, 0, v118
	v_max_f32_e32 v119, 0, v119
	v_max_f32_e32 v120, 0, v120
	v_max_f32_e32 v121, 0, v121
	v_pk_mul_f32 v[118:119], v[118:119], v[118:119]
	v_pk_mul_f32 v[120:121], v[120:121], v[120:121]
	v_cvt_pk_bf16_f32 v118, v118, v119
	v_cvt_pk_bf16_f32 v119, v120, v121
	ds_write_b64 v134, v[118:119] offset:4288
	v_mul_f32_e32 v122, v122, v144
	v_mul_f32_e32 v123, v123, v144
	v_mul_f32_e32 v124, v124, v144
	v_mul_f32_e32 v125, v125, v144
	v_max_f32_e32 v122, 0, v122
	v_max_f32_e32 v123, 0, v123
	v_max_f32_e32 v124, 0, v124
	v_max_f32_e32 v125, 0, v125
	v_pk_mul_f32 v[122:123], v[122:123], v[122:123]
	v_pk_mul_f32 v[124:125], v[124:125], v[124:125]
	v_cvt_pk_bf16_f32 v122, v122, v123
	v_cvt_pk_bf16_f32 v123, v124, v125
	ds_write_b64 v134, v[122:123] offset:96
	v_mul_f32_e32 v126, v126, v145
	v_mul_f32_e32 v127, v127, v145
	v_mul_f32_e32 v128, v128, v145
	v_mul_f32_e32 v129, v129, v145
	v_max_f32_e32 v126, 0, v126
	v_max_f32_e32 v127, 0, v127
	v_max_f32_e32 v128, 0, v128
	v_max_f32_e32 v129, 0, v129
	v_pk_mul_f32 v[126:127], v[126:127], v[126:127]
	v_pk_mul_f32 v[128:129], v[128:129], v[128:129]
	v_cvt_pk_bf16_f32 v126, v126, v127
	v_cvt_pk_bf16_f32 v127, v128, v129
	ds_write_b64 v134, v[126:127] offset:4320
	s_waitcnt lgkmcnt(0)
	s_barrier
	ds_read_b64 v[114:115], v135
	ds_read_b64 v[116:117], v135 offset:4224
	ds_read_b64 v[118:119], v135 offset:8448
	ds_read_b64 v[120:121], v135 offset:12672
	ds_read_b64 v[122:123], v135 offset:16896
	ds_read_b64 v[124:125], v135 offset:21120
	ds_read_b64 v[126:127], v135 offset:25344
	ds_read_b64 v[128:129], v135 offset:29568
	s_waitcnt lgkmcnt(7)
	global_store_dwordx2 v132, v[114:115], s[6:7]
	s_waitcnt lgkmcnt(6)
	v_add_u32_e32 v136, 0x20000, v132
	global_store_dwordx2 v136, v[116:117], s[6:7]
	s_waitcnt lgkmcnt(5)
	v_add_u32_e32 v136, 0x40000, v132
	global_store_dwordx2 v136, v[118:119], s[6:7]
	s_waitcnt lgkmcnt(4)
	v_add_u32_e32 v136, 0x60000, v132
	global_store_dwordx2 v136, v[120:121], s[6:7]
	s_waitcnt lgkmcnt(3)
	v_add_u32_e32 v136, 0x80000, v132
	global_store_dwordx2 v136, v[122:123], s[6:7]
	s_waitcnt lgkmcnt(2)
	v_add_u32_e32 v136, 0xa0000, v132
	global_store_dwordx2 v136, v[124:125], s[6:7]
	s_waitcnt lgkmcnt(1)
	v_add_u32_e32 v136, 0xc0000, v132
	global_store_dwordx2 v136, v[126:127], s[6:7]
	s_waitcnt lgkmcnt(0)
	v_add_u32_e32 v136, 0xe0000, v132
	global_store_dwordx2 v136, v[128:129], s[6:7]
	s_barrier
; DI unsigned pk2(float a, float b) { f32x2 v = {a, b}; bf2_t r = __builtin_convertvector(v, bf2_t); return __builtin_bit_cast(unsigned, r); }
; template <int MODE>
; DI void gemm_tile(const Params& p, const bf16_t* __restrict__ A, const bf16_t* __restrict__ Bt, int K, int brow, int bcol, int mp, int nt, bool vt, char* smem) {
;     ...
;   for (int ai = 0; ai < 2; ++ai)
; #pragma unroll
;     for (int bj = 0; bj < 2; ++bj) {
; #pragma unroll
;       for (int m = 0; m < 4; ++m)
; #pragma unroll
;         for (int n = 0; n < 2; ++n) *(f32x4*)(st + (wc * 32 + n * 16 + fr) * 132 + wr * 64 + m * 16 + fq * 4) = acc[ai][bj][m][n];
;       __syncthreads();
;     ...
;         } else if (MODE == MODE_UP) {
;           const int tok = m0 + bj * 128 + y, col = n0 + ai * 128 + x4;
;           const float rs = rsl[bj * 128 + y];
;           const float a0 = fmaxf(v[0] * rs, 0.f), a1 = fmaxf(v[1] * rs, 0.f), a2 = fmaxf(v[2] * rs, 0.f), a3 = fmaxf(v[3] * rs, 0.f);
;           u32x2 o = {pk2(a0 * a0, a1 * a1), pk2(a2 * a2, a3 * a3)};
;           *(u32x2*)((bf16_t*)(p.ws + OFF_U) + (size_t)tok * DFF + col) = o;
	v_mul_f32_e32 v66, v66, v146
	v_mul_f32_e32 v67, v67, v146
	v_mul_f32_e32 v68, v68, v146
	v_mul_f32_e32 v69, v69, v146
	v_max_f32_e32 v66, 0, v66
	v_max_f32_e32 v67, 0, v67
	v_max_f32_e32 v68, 0, v68
	v_max_f32_e32 v69, 0, v69
	v_pk_mul_f32 v[66:67], v[66:67], v[66:67]
	v_pk_mul_f32 v[68:69], v[68:69], v[68:69]
	v_cvt_pk_bf16_f32 v66, v66, v67
	v_cvt_pk_bf16_f32 v67, v68, v69
	ds_write_b64 v134, v[66:67]
	v_mul_f32_e32 v70, v70, v147
	v_mul_f32_e32 v71, v71, v147
	v_mul_f32_e32 v72, v72, v147
	v_mul_f32_e32 v73, v73, v147
	v_max_f32_e32 v70, 0, v70
	v_max_f32_e32 v71, 0, v71
	v_max_f32_e32 v72, 0, v72
	v_max_f32_e32 v73, 0, v73
	v_pk_mul_f32 v[70:71], v[70:71], v[70:71]
	v_pk_mul_f32 v[72:73], v[72:73], v[72:73]
	v_cvt_pk_bf16_f32 v70, v70, v71
	v_cvt_pk_bf16_f32 v71, v72, v73
	ds_write_b64 v134, v[70:71] offset:4224
	v_mul_f32_e32 v74, v74, v146
	v_mul_f32_e32 v75, v75, v146
	v_mul_f32_e32 v76, v76, v146
	v_mul_f32_e32 v77, v77, v146
	v_max_f32_e32 v74, 0, v74
	v_max_f32_e32 v75, 0, v75
	v_max_f32_e32 v76, 0, v76
	v_max_f32_e32 v77, 0, v77
	v_pk_mul_f32 v[74:75], v[74:75], v[74:75]
	v_pk_mul_f32 v[76:77], v[76:77], v[76:77]
	v_cvt_pk_bf16_f32 v74, v74, v75
	v_cvt_pk_bf16_f32 v75, v76, v77
	ds_write_b64 v134, v[74:75] offset:32
	v_mul_f32_e32 v78, v78, v147
	v_mul_f32_e32 v79, v79, v147
	v_mul_f32_e32 v80, v80, v147
	v_mul_f32_e32 v81, v81, v147
	v_max_f32_e32 v78, 0, v78
	v_max_f32_e32 v79, 0, v79
	v_max_f32_e32 v80, 0, v80
	v_max_f32_e32 v81, 0, v81
	v_pk_mul_f32 v[78:79], v[78:79], v[78:79]
	v_pk_mul_f32 v[80:81], v[80:81], v[80:81]
	v_cvt_pk_bf16_f32 v78, v78, v79
	v_cvt_pk_bf16_f32 v79, v80, v81
	ds_write_b64 v134, v[78:79] offset:4256
	v_mul_f32_e32 v82, v82, v146
	v_mul_f32_e32 v83, v83, v146
	v_mul_f32_e32 v84, v84, v146
	v_mul_f32_e32 v85, v85, v146
	v_max_f32_e32 v82, 0, v82
	v_max_f32_e32 v83, 0, v83
	v_max_f32_e32 v84, 0, v84
	v_max_f32_e32 v85, 0, v85
	v_pk_mul_f32 v[82:83], v[82:83], v[82:83]
	v_pk_mul_f32 v[84:85], v[84:85], v[84:85]
	v_cvt_pk_bf16_f32 v82, v82, v83
	v_cvt_pk_bf16_f32 v83, v84, v85
	ds_write_b64 v134, v[82:83] offset:64
	v_mul_f32_e32 v86, v86, v147
	v_mul_f32_e32 v87, v87, v147
	v_mul_f32_e32 v88, v88, v147
	v_mul_f32_e32 v89, v89, v147
	v_max_f32_e32 v86, 0, v86
	v_max_f32_e32 v87, 0, v87
	v_max_f32_e32 v88, 0, v88
	v_max_f32_e32 v89, 0, v89
	v_pk_mul_f32 v[86:87], v[86:87], v[86:87]
	v_pk_mul_f32 v[88:89], v[88:89], v[88:89]
	v_cvt_pk_bf16_f32 v86, v86, v87
	v_cvt_pk_bf16_f32 v87, v88, v89
	ds_write_b64 v134, v[86:87] offset:4288
	v_mul_f32_e32 v90, v90, v146
	v_mul_f32_e32 v91, v91, v146
	v_mul_f32_e32 v92, v92, v146
	v_mul_f32_e32 v93, v93, v146
	v_max_f32_e32 v90, 0, v90
	v_max_f32_e32 v91, 0, v91
	v_max_f32_e32 v92, 0, v92
	v_max_f32_e32 v93, 0, v93
	v_pk_mul_f32 v[90:91], v[90:91], v[90:91]
	v_pk_mul_f32 v[92:93], v[92:93], v[92:93]
	v_cvt_pk_bf16_f32 v90, v90, v91
	v_cvt_pk_bf16_f32 v91, v92, v93
	ds_write_b64 v134, v[90:91] offset:96
	v_mul_f32_e32 v94, v94, v147
	v_mul_f32_e32 v95, v95, v147
	v_mul_f32_e32 v96, v96, v147
	v_mul_f32_e32 v97, v97, v147
	v_max_f32_e32 v94, 0, v94
	v_max_f32_e32 v95, 0, v95
	v_max_f32_e32 v96, 0, v96
	v_max_f32_e32 v97, 0, v97
	v_pk_mul_f32 v[94:95], v[94:95], v[94:95]
	v_pk_mul_f32 v[96:97], v[96:97], v[96:97]
	v_cvt_pk_bf16_f32 v94, v94, v95
	v_cvt_pk_bf16_f32 v95, v96, v97
	ds_write_b64 v134, v[94:95] offset:4320
	s_waitcnt lgkmcnt(0)
	s_barrier
	ds_read_b64 v[82:83], v135
	ds_read_b64 v[84:85], v135 offset:4224
	ds_read_b64 v[86:87], v135 offset:8448
	ds_read_b64 v[88:89], v135 offset:12672
	ds_read_b64 v[90:91], v135 offset:16896
	ds_read_b64 v[92:93], v135 offset:21120
	ds_read_b64 v[94:95], v135 offset:25344
	ds_read_b64 v[96:97], v135 offset:29568
	s_waitcnt lgkmcnt(7)
	v_add_u32_e32 v136, 0x100000, v132
	global_store_dwordx2 v136, v[82:83], s[6:7]
	s_waitcnt lgkmcnt(6)
	v_add_u32_e32 v136, 0x120000, v132
	global_store_dwordx2 v136, v[84:85], s[6:7]
	s_waitcnt lgkmcnt(5)
	v_add_u32_e32 v136, 0x140000, v132
	global_store_dwordx2 v136, v[86:87], s[6:7]
	s_waitcnt lgkmcnt(4)
	v_add_u32_e32 v136, 0x160000, v132
	global_store_dwordx2 v136, v[88:89], s[6:7]
	s_waitcnt lgkmcnt(3)
	v_add_u32_e32 v136, 0x180000, v132
	global_store_dwordx2 v136, v[90:91], s[6:7]
	s_waitcnt lgkmcnt(2)
	v_add_u32_e32 v136, 0x1a0000, v132
	global_store_dwordx2 v136, v[92:93], s[6:7]
	s_waitcnt lgkmcnt(1)
	v_add_u32_e32 v136, 0x1c0000, v132
	global_store_dwordx2 v136, v[94:95], s[6:7]
	s_waitcnt lgkmcnt(0)
	v_add_u32_e32 v136, 0x1e0000, v132
	global_store_dwordx2 v136, v[96:97], s[6:7]
	s_barrier
; DI unsigned pk2(float a, float b) { f32x2 v = {a, b}; bf2_t r = __builtin_convertvector(v, bf2_t); return __builtin_bit_cast(unsigned, r); }
; template <int MODE>
; DI void gemm_tile(const Params& p, const bf16_t* __restrict__ A, const bf16_t* __restrict__ Bt, int K, int brow, int bcol, int mp, int nt, bool vt, char* smem) {
;     ...
;   for (int ai = 0; ai < 2; ++ai)
; #pragma unroll
;     for (int bj = 0; bj < 2; ++bj) {
; #pragma unroll
;       for (int m = 0; m < 4; ++m)
; #pragma unroll
;         for (int n = 0; n < 2; ++n) *(f32x4*)(st + (wc * 32 + n * 16 + fr) * 132 + wr * 64 + m * 16 + fq * 4) = acc[ai][bj][m][n];
;       __syncthreads();
;     ...
;         } else if (MODE == MODE_UP) {
;           const int tok = m0 + bj * 128 + y, col = n0 + ai * 128 + x4;
;           const float rs = rsl[bj * 128 + y];
;           const float a0 = fmaxf(v[0] * rs, 0.f), a1 = fmaxf(v[1] * rs, 0.f), a2 = fmaxf(v[2] * rs, 0.f), a3 = fmaxf(v[3] * rs, 0.f);
;           u32x2 o = {pk2(a0 * a0, a1 * a1), pk2(a2 * a2, a3 * a3)};
;           *(u32x2*)((bf16_t*)(p.ws + OFF_U) + (size_t)tok * DFF + col) = o;
	v_mul_f32_e32 v34, v34, v144
	v_mul_f32_e32 v35, v35, v144
	v_mul_f32_e32 v36, v36, v144
	v_mul_f32_e32 v37, v37, v144
	v_max_f32_e32 v34, 0, v34
	v_max_f32_e32 v35, 0, v35
	v_max_f32_e32 v36, 0, v36
	v_max_f32_e32 v37, 0, v37
	v_pk_mul_f32 v[34:35], v[34:35], v[34:35]
	v_pk_mul_f32 v[36:37], v[36:37], v[36:37]
	v_cvt_pk_bf16_f32 v34, v34, v35
	v_cvt_pk_bf16_f32 v35, v36, v37
	ds_write_b64 v134, v[34:35]
	v_mul_f32_e32 v38, v38, v145
	v_mul_f32_e32 v39, v39, v145
	v_mul_f32_e32 v40, v40, v145
	v_mul_f32_e32 v41, v41, v145
	v_max_f32_e32 v38, 0, v38
	v_max_f32_e32 v39, 0, v39
	v_max_f32_e32 v40, 0, v40
	v_max_f32_e32 v41, 0, v41
	v_pk_mul_f32 v[38:39], v[38:39], v[38:39]
	v_pk_mul_f32 v[40:41], v[40:41], v[40:41]
	v_cvt_pk_bf16_f32 v38, v38, v39
	v_cvt_pk_bf16_f32 v39, v40, v41
	ds_write_b64 v134, v[38:39] offset:4224
	v_mul_f32_e32 v42, v42, v144
	v_mul_f32_e32 v43, v43, v144
	v_mul_f32_e32 v44, v44, v144
	v_mul_f32_e32 v45, v45, v144
	v_max_f32_e32 v42, 0, v42
	v_max_f32_e32 v43, 0, v43
	v_max_f32_e32 v44, 0, v44
	v_max_f32_e32 v45, 0, v45
	v_pk_mul_f32 v[42:43], v[42:43], v[42:43]
	v_pk_mul_f32 v[44:45], v[44:45], v[44:45]
	v_cvt_pk_bf16_f32 v42, v42, v43
	v_cvt_pk_bf16_f32 v43, v44, v45
	ds_write_b64 v134, v[42:43] offset:32
	v_mul_f32_e32 v46, v46, v145
	v_mul_f32_e32 v47, v47, v145
	v_mul_f32_e32 v48, v48, v145
	v_mul_f32_e32 v49, v49, v145
	v_max_f32_e32 v46, 0, v46
	v_max_f32_e32 v47, 0, v47
	v_max_f32_e32 v48, 0, v48
	v_max_f32_e32 v49, 0, v49
	v_pk_mul_f32 v[46:47], v[46:47], v[46:47]
	v_pk_mul_f32 v[48:49], v[48:49], v[48:49]
	v_cvt_pk_bf16_f32 v46, v46, v47
	v_cvt_pk_bf16_f32 v47, v48, v49
	ds_write_b64 v134, v[46:47] offset:4256
	v_mul_f32_e32 v50, v50, v144
	v_mul_f32_e32 v51, v51, v144
	v_mul_f32_e32 v52, v52, v144
	v_mul_f32_e32 v53, v53, v144
	v_max_f32_e32 v50, 0, v50
	v_max_f32_e32 v51, 0, v51
	v_max_f32_e32 v52, 0, v52
	v_max_f32_e32 v53, 0, v53
	v_pk_mul_f32 v[50:51], v[50:51], v[50:51]
	v_pk_mul_f32 v[52:53], v[52:53], v[52:53]
	v_cvt_pk_bf16_f32 v50, v50, v51
	v_cvt_pk_bf16_f32 v51, v52, v53
	ds_write_b64 v134, v[50:51] offset:64
	v_mul_f32_e32 v54, v54, v145
	v_mul_f32_e32 v55, v55, v145
	v_mul_f32_e32 v56, v56, v145
	v_mul_f32_e32 v57, v57, v145
	v_max_f32_e32 v54, 0, v54
	v_max_f32_e32 v55, 0, v55
	v_max_f32_e32 v56, 0, v56
	v_max_f32_e32 v57, 0, v57
	v_pk_mul_f32 v[54:55], v[54:55], v[54:55]
	v_pk_mul_f32 v[56:57], v[56:57], v[56:57]
	v_cvt_pk_bf16_f32 v54, v54, v55
	v_cvt_pk_bf16_f32 v55, v56, v57
	ds_write_b64 v134, v[54:55] offset:4288
	v_mul_f32_e32 v58, v58, v144
	v_mul_f32_e32 v59, v59, v144
	v_mul_f32_e32 v60, v60, v144
	v_mul_f32_e32 v61, v61, v144
	v_max_f32_e32 v58, 0, v58
	v_max_f32_e32 v59, 0, v59
	v_max_f32_e32 v60, 0, v60
	v_max_f32_e32 v61, 0, v61
	v_pk_mul_f32 v[58:59], v[58:59], v[58:59]
	v_pk_mul_f32 v[60:61], v[60:61], v[60:61]
	v_cvt_pk_bf16_f32 v58, v58, v59
	v_cvt_pk_bf16_f32 v59, v60, v61
	ds_write_b64 v134, v[58:59] offset:96
	v_mul_f32_e32 v62, v62, v145
	v_mul_f32_e32 v63, v63, v145
	v_mul_f32_e32 v64, v64, v145
	v_mul_f32_e32 v65, v65, v145
	v_max_f32_e32 v62, 0, v62
	v_max_f32_e32 v63, 0, v63
	v_max_f32_e32 v64, 0, v64
	v_max_f32_e32 v65, 0, v65
	v_pk_mul_f32 v[62:63], v[62:63], v[62:63]
	v_pk_mul_f32 v[64:65], v[64:65], v[64:65]
	v_cvt_pk_bf16_f32 v62, v62, v63
	v_cvt_pk_bf16_f32 v63, v64, v65
	ds_write_b64 v134, v[62:63] offset:4320
	s_waitcnt lgkmcnt(0)
	s_barrier
	ds_read_b64 v[50:51], v135
	ds_read_b64 v[52:53], v135 offset:4224
	ds_read_b64 v[54:55], v135 offset:8448
	ds_read_b64 v[56:57], v135 offset:12672
	ds_read_b64 v[58:59], v135 offset:16896
	ds_read_b64 v[60:61], v135 offset:21120
	ds_read_b64 v[62:63], v135 offset:25344
	ds_read_b64 v[64:65], v135 offset:29568
	s_waitcnt lgkmcnt(7)
	global_store_dwordx2 v132, v[50:51], s[6:7] offset:256
	s_waitcnt lgkmcnt(6)
	v_add_u32_e32 v136, 0x20000, v132
	global_store_dwordx2 v136, v[52:53], s[6:7] offset:256
	s_waitcnt lgkmcnt(5)
	v_add_u32_e32 v136, 0x40000, v132
	global_store_dwordx2 v136, v[54:55], s[6:7] offset:256
	s_waitcnt lgkmcnt(4)
	v_add_u32_e32 v136, 0x60000, v132
	global_store_dwordx2 v136, v[56:57], s[6:7] offset:256
	s_waitcnt lgkmcnt(3)
	v_add_u32_e32 v136, 0x80000, v132
	global_store_dwordx2 v136, v[58:59], s[6:7] offset:256
	s_waitcnt lgkmcnt(2)
	v_add_u32_e32 v136, 0xa0000, v132
	global_store_dwordx2 v136, v[60:61], s[6:7] offset:256
	s_waitcnt lgkmcnt(1)
	v_add_u32_e32 v136, 0xc0000, v132
	global_store_dwordx2 v136, v[62:63], s[6:7] offset:256
	s_waitcnt lgkmcnt(0)
	v_add_u32_e32 v136, 0xe0000, v132
	global_store_dwordx2 v136, v[64:65], s[6:7] offset:256
	s_barrier
; DI unsigned pk2(float a, float b) { f32x2 v = {a, b}; bf2_t r = __builtin_convertvector(v, bf2_t); return __builtin_bit_cast(unsigned, r); }
; DI f32x4 unpk4(u32x2 u) { f32x4 r = {__uint_as_float(u[0] << 16), __uint_as_float(u[0] & 0xffff0000u), __uint_as_float(u[1] << 16), __uint_as_float(u[1] & 0xffff0000u)}; return r; }
; template <int MODE>
; DI void gemm_tile(const Params& p, const bf16_t* __restrict__ A, const bf16_t* __restrict__ Bt, int K, int brow, int bcol, int mp, int nt, bool vt, char* smem) {
;     ...
;         } else if (MODE == MODE_UP) {
;           const int tok = m0 + bj * 128 + y, col = n0 + ai * 128 + x4;
;           const float rs = rsl[bj * 128 + y];
;           const float a0 = fmaxf(v[0] * rs, 0.f), a1 = fmaxf(v[1] * rs, 0.f), a2 = fmaxf(v[2] * rs, 0.f), a3 = fmaxf(v[3] * rs, 0.f);
;           u32x2 o = {pk2(a0 * a0, a1 * a1), pk2(a2 * a2, a3 * a3)};
;           *(u32x2*)((bf16_t*)(p.ws + OFF_U) + (size_t)tok * DFF + col) = o;
;         } else {
;           const int tok = m0 + bj * 128 + y, col = n0 + ai * 128 + x4;
;           const f32x4 xs = unpk4(xo[pq]) + v;
;           u32x2 o = {pk2(xs[0], xs[1]), pk2(xs[2], xs[3])};
;           *(u32x2*)((bf16_t*)(p.ws + OFF_XB) + (size_t)tok * DM + col) = o;
;           const f32x4 xn = unpk4(o);
;           float ss = xn[0] * xn[0] + xn[1] * xn[1] + xn[2] * xn[2] + xn[3] * xn[3];
; #pragma unroll
;           for (int o2 = 16; o2 > 0; o2 >>= 1) ss += __shfl_xor(ss, o2);
;           if ((tid & 31) == 0) ((float*)(p.ws + (MODE == MODE_OUT ? OFF_SSB : OFF_SSA)))[(size_t)tok * 8 + nt * 2 + ai] = ss;
;         }
;       }
;       }
;       __syncthreads();
; template <int MODE>
; DI void phase_gemm(const Params& p, int l, char* smem) {
;     ...
;   for (int L = xmap ? (int)(blockIdx.x >> 3) : (int)blockIdx.x; L < tot; L += nb) {
	v_mul_f32_e32 v2, v2, v146
	v_mul_f32_e32 v3, v3, v146
	v_mul_f32_e32 v4, v4, v146
	v_mul_f32_e32 v5, v5, v146
	v_max_f32_e32 v2, 0, v2
	v_max_f32_e32 v3, 0, v3
	v_max_f32_e32 v4, 0, v4
	v_max_f32_e32 v5, 0, v5
	v_pk_mul_f32 v[2:3], v[2:3], v[2:3]
	v_pk_mul_f32 v[4:5], v[4:5], v[4:5]
	v_cvt_pk_bf16_f32 v2, v2, v3
	v_cvt_pk_bf16_f32 v3, v4, v5
	ds_write_b64 v134, v[2:3]
	v_mul_f32_e32 v6, v6, v147
	v_mul_f32_e32 v7, v7, v147
	v_mul_f32_e32 v8, v8, v147
	v_mul_f32_e32 v9, v9, v147
	v_max_f32_e32 v6, 0, v6
	v_max_f32_e32 v7, 0, v7
	v_max_f32_e32 v8, 0, v8
	v_max_f32_e32 v9, 0, v9
	v_pk_mul_f32 v[6:7], v[6:7], v[6:7]
	v_pk_mul_f32 v[8:9], v[8:9], v[8:9]
	v_cvt_pk_bf16_f32 v6, v6, v7
	v_cvt_pk_bf16_f32 v7, v8, v9
	ds_write_b64 v134, v[6:7] offset:4224
	v_mul_f32_e32 v10, v10, v146
	v_mul_f32_e32 v11, v11, v146
	v_mul_f32_e32 v12, v12, v146
	v_mul_f32_e32 v13, v13, v146
	v_max_f32_e32 v10, 0, v10
	v_max_f32_e32 v11, 0, v11
	v_max_f32_e32 v12, 0, v12
	v_max_f32_e32 v13, 0, v13
	v_pk_mul_f32 v[10:11], v[10:11], v[10:11]
	v_pk_mul_f32 v[12:13], v[12:13], v[12:13]
	v_cvt_pk_bf16_f32 v10, v10, v11
	v_cvt_pk_bf16_f32 v11, v12, v13
	ds_write_b64 v134, v[10:11] offset:32
	v_mul_f32_e32 v14, v14, v147
	v_mul_f32_e32 v15, v15, v147
	v_mul_f32_e32 v16, v16, v147
	v_mul_f32_e32 v17, v17, v147
	v_max_f32_e32 v14, 0, v14
	v_max_f32_e32 v15, 0, v15
	v_max_f32_e32 v16, 0, v16
	v_max_f32_e32 v17, 0, v17
	v_pk_mul_f32 v[14:15], v[14:15], v[14:15]
	v_pk_mul_f32 v[16:17], v[16:17], v[16:17]
	v_cvt_pk_bf16_f32 v14, v14, v15
	v_cvt_pk_bf16_f32 v15, v16, v17
	ds_write_b64 v134, v[14:15] offset:4256
	v_mul_f32_e32 v18, v18, v146
	v_mul_f32_e32 v19, v19, v146
	v_mul_f32_e32 v20, v20, v146
	v_mul_f32_e32 v21, v21, v146
	v_max_f32_e32 v18, 0, v18
	v_max_f32_e32 v19, 0, v19
	v_max_f32_e32 v20, 0, v20
	v_max_f32_e32 v21, 0, v21
	v_pk_mul_f32 v[18:19], v[18:19], v[18:19]
	v_pk_mul_f32 v[20:21], v[20:21], v[20:21]
	v_cvt_pk_bf16_f32 v18, v18, v19
	v_cvt_pk_bf16_f32 v19, v20, v21
	ds_write_b64 v134, v[18:19] offset:64
	v_mul_f32_e32 v22, v22, v147
	v_mul_f32_e32 v23, v23, v147
	v_mul_f32_e32 v24, v24, v147
	v_mul_f32_e32 v25, v25, v147
	v_max_f32_e32 v22, 0, v22
	v_max_f32_e32 v23, 0, v23
	v_max_f32_e32 v24, 0, v24
	v_max_f32_e32 v25, 0, v25
	v_pk_mul_f32 v[22:23], v[22:23], v[22:23]
	v_pk_mul_f32 v[24:25], v[24:25], v[24:25]
	v_cvt_pk_bf16_f32 v22, v22, v23
	v_cvt_pk_bf16_f32 v23, v24, v25
	ds_write_b64 v134, v[22:23] offset:4288
	v_mul_f32_e32 v26, v26, v146
	v_mul_f32_e32 v27, v27, v146
	v_mul_f32_e32 v28, v28, v146
	v_mul_f32_e32 v29, v29, v146
	v_max_f32_e32 v26, 0, v26
	v_max_f32_e32 v27, 0, v27
	v_max_f32_e32 v28, 0, v28
	v_max_f32_e32 v29, 0, v29
	v_pk_mul_f32 v[26:27], v[26:27], v[26:27]
	v_pk_mul_f32 v[28:29], v[28:29], v[28:29]
	v_cvt_pk_bf16_f32 v26, v26, v27
	v_cvt_pk_bf16_f32 v27, v28, v29
	ds_write_b64 v134, v[26:27] offset:96
	v_mul_f32_e32 v30, v30, v147
	v_mul_f32_e32 v31, v31, v147
	v_mul_f32_e32 v32, v32, v147
	v_mul_f32_e32 v33, v33, v147
	v_max_f32_e32 v30, 0, v30
	v_max_f32_e32 v31, 0, v31
	v_max_f32_e32 v32, 0, v32
	v_max_f32_e32 v33, 0, v33
	v_pk_mul_f32 v[30:31], v[30:31], v[30:31]
	v_pk_mul_f32 v[32:33], v[32:33], v[32:33]
	v_cvt_pk_bf16_f32 v30, v30, v31
	v_cvt_pk_bf16_f32 v31, v32, v33
	ds_write_b64 v134, v[30:31] offset:4320
	s_waitcnt lgkmcnt(0)
	s_barrier
	ds_read_b64 v[18:19], v135
	ds_read_b64 v[20:21], v135 offset:4224
	ds_read_b64 v[22:23], v135 offset:8448
	ds_read_b64 v[24:25], v135 offset:12672
	ds_read_b64 v[26:27], v135 offset:16896
	ds_read_b64 v[28:29], v135 offset:21120
	ds_read_b64 v[30:31], v135 offset:25344
	ds_read_b64 v[32:33], v135 offset:29568
	s_waitcnt lgkmcnt(7)
	v_add_u32_e32 v136, 0x100000, v132
	global_store_dwordx2 v136, v[18:19], s[6:7] offset:256
	s_waitcnt lgkmcnt(6)
	v_add_u32_e32 v136, 0x120000, v132
	global_store_dwordx2 v136, v[20:21], s[6:7] offset:256
	s_waitcnt lgkmcnt(5)
	v_add_u32_e32 v136, 0x140000, v132
	global_store_dwordx2 v136, v[22:23], s[6:7] offset:256
	s_waitcnt lgkmcnt(4)
	v_add_u32_e32 v136, 0x160000, v132
	global_store_dwordx2 v136, v[24:25], s[6:7] offset:256
	s_waitcnt lgkmcnt(3)
	v_add_u32_e32 v136, 0x180000, v132
	global_store_dwordx2 v136, v[26:27], s[6:7] offset:256
	s_waitcnt lgkmcnt(2)
	v_add_u32_e32 v136, 0x1a0000, v132
	global_store_dwordx2 v136, v[28:29], s[6:7] offset:256
	s_waitcnt lgkmcnt(1)
	v_add_u32_e32 v136, 0x1c0000, v132
	global_store_dwordx2 v136, v[30:31], s[6:7] offset:256
	s_waitcnt lgkmcnt(0)
	v_add_u32_e32 v136, 0x1e0000, v132
	global_store_dwordx2 v136, v[32:33], s[6:7] offset:256
	s_add_i32 s22, s22, s60
	v_readlane_b32 s0, v246, 4
	s_cmp_ge_i32 s22, s0
	s_nop 0
	s_cbranch_scc0 .LBB0_29

; DI unsigned pk2(float a, float b) { f32x2 v = {a, b}; bf2_t r = __builtin_convertvector(v, bf2_t); return __builtin_bit_cast(unsigned, r); }
; template <int MODE>
; DI void gemm_tile(const Params& p, const bf16_t* __restrict__ A, const bf16_t* __restrict__ Bt, int K, int brow, int bcol, int mp, int nt, bool vt, char* smem) {
;     ...
;         for (int n = 0; n < 2; ++n) *(f32x4*)(st + (wc * 32 + n * 16 + fr) * 132 + wr * 64 + m * 16 + fq * 4) = acc[ai][bj][m][n];
;       __syncthreads();
; #pragma unroll 1
;       for (int pg = 0; pg < 2; ++pg) {
;       u32x2 xo[4];
;       if (RESID) {
; #pragma unroll
;         for (int pq = 0; pq < 4; ++pq) xo[pq] = xnx[pq];
;         const int q = ai * 2 + bj, nq = pg ? q + 1 : q, npg = pg ^ 1;
;         if (nq < 4) {
;           const int nai = nq >> 1, nbj = nq & 1;
; #pragma unroll
;           for (int pq = 0; pq < 4; ++pq)
;             xnx[pq] = *(const u32x2*)((const bf16_t*)(p.ws + OFF_XB) + (size_t)(m0 + nbj * 128 + (npg * 4 + pq) * 16 + (tid >> 5)) * DM + n0 + nai * 128 + (tid & 31) * 4);
;         }
;       }
; #pragma unroll
;       for (int pq = 0; pq < 4; ++pq) {
;         const int pass = pg * 4 + pq;
;         const int y = pass * 16 + (tid >> 5), x4 = (tid & 31) * 4;
;         const f32x4 v = *(const f32x4*)(st + y * 132 + x4);
;         if (MODE == MODE_PROJ) {
;           if (vt) {
;             const int vrow = (nt - 8) * 256 + bj * 128 + y, tk = m0 + ai * 128 + x4, b = tk >> 11, sq = tk & 2047;
;             const f32x4 rr = *(const f32x4*)(rsl + ai * 128 + x4);
;             u32x2 o = {pk2(v[0] * rr[0], v[1] * rr[1]), pk2(v[2] * rr[2], v[3] * rr[3])};
;             *(u32x2*)((bf16_t*)(p.ws + OFF_VT) + ((size_t)(b * VROWS + vrow)) * SEQ + sq) = o;
;           } else {
;             const int tok = m0 + bj * 128 + y, col = n0 + ai * 128 + x4;
;             const float rs = rsl[bj * 128 + y];
;             if (col < QKW) {
;               u32x2 o = {pk2(v[0] * rs, v[1] * rs), pk2(v[2] * rs, v[3] * rs)};
;               *(u32x2*)((bf16_t*)(p.ws + OFF_QK) + (size_t)tok * QKW + col) = o;
;             } else if (col < QKW + 16) {
;               f32x4 o = {v[0] * rs, v[1] * rs, v[2] * rs, v[3] * rs};
;               *(f32x4*)((float*)(p.ws + OFF_GATE) + (size_t)tok * 16 + (col - QKW)) = o;
;             }
;           }
.LBB0_590:
	s_or_b64 exec, exec, s[2:3]
	s_movk_i32 s2, 0xff00
	v_and_or_b32 v133, v0, s2, v141
	s_lshr_b32 s2, s19, 3
	s_lshl_b32 s1, s20, 8
	v_and_b32_e32 v134, 0x7c, v130
	s_mulk_i32 s2, 0x300
	v_lshl_or_b32 v135, v131, 5, v142
	v_ashrrev_i32_e32 v131, 5, v0
	v_or_b32_e32 v0, s1, v134
	s_add_i32 s1, s1, s2
	s_and_b32 s2, s0, 0x700
	v_or_b32_e32 v138, s2, v134
	s_movk_i32 s2, 0x77f
	v_cmp_lt_i32_e64 s[4:5], s2, v0
	s_movk_i32 s2, 0x790
	v_cmp_gt_u32_e64 s[6:7], s2, v0
	v_readlane_b32 s2, v246, 14
	v_lshlrev_b32_e32 v130, 2, v134
	v_ashrrev_i32_e32 v137, 31, v0
	v_mov_b32_e32 v136, v0
	v_mul_u32_u24_e32 v134, 0x210, v135
	v_mad_u32_u24 v135, v135, s33, v133
	v_readlane_b32 s3, v246, 15
	s_barrier
	ds_write_b128 v135, v[98:101]
	ds_write_b128 v135, v[102:105] offset:8448
	ds_write_b128 v135, v[106:109] offset:64
	ds_write_b128 v135, v[110:113] offset:8512
	ds_write_b128 v135, v[114:117] offset:128
	ds_write_b128 v135, v[118:121] offset:8576
	ds_write_b128 v135, v[122:125] offset:192
	ds_write_b128 v135, v[126:129] offset:8640
	v_lshl_add_u64 v[106:107], v[136:137], 1, s[2:3]
	v_readlane_b32 s2, v246, 20
	v_lshlrev_b32_e32 v98, 1, v138
	v_mov_b32_e32 v99, v1
	v_readlane_b32 s3, v246, 21
	v_or_b32_e32 v132, 0x20400, v130
	s_addk_i32 s1, 0xf800
	v_lshl_add_u64 v[102:103], v[0:1], 2, s[78:79]
	v_lshl_add_u64 v[104:105], s[2:3], 0, v[98:99]
	s_mov_b32 s12, 0
	s_mov_b64 s[10:11], -1
	s_waitcnt lgkmcnt(0)
	s_barrier
	s_branch .LBB0_592
